# GEMM unit loops: the duplicate accumulator clear runs only on the K==0 path, and the vmcnt(0) that drained the epilogue stores before the clear is gone
# speedup vs baseline: 1.0174x; 1.0021x over previous
; template <class Epi, class Sched>
; __device__ __forceinline__ void gemm_phase(LAS unsigned char* lds, const Gemm g, const Sched& S, const Epi& E) {
;     ...
;         for (int t = 0; t < nt; t += 2) {
;             const bool last = (t == nt - 2);
;             const char* a1 = cA + (size_t)(t + 1) * kstep;
;             const char* a2 = last ? nA : cA + (size_t)(t + 2) * kstep; const char* b2 = last ? nB : cB + (size_t)(t + 2) * kstep;
;             const char* a3 = a2 + kstep; const char* b3 = b2 + kstep;
;     ...
; #pragma unroll
;         for (int a = 0; a < 2; ++a)
; #pragma unroll
;             for (int b = 0; b < 2; ++b)
; #pragma unroll
;                 for (int m = 0; m < 4; ++m)
; #pragma unroll
;                     for (int n = 0; n < 2; ++n) acc[a][b][m][n] = (f32x4){0.f, 0.f, 0.f, 0.f};
;         cur = nxt; cA = nA; cB = nB; ++ui;
.LBB0_176:
	s_andn2_b64 vcc, exec, s[56:57]
	s_cbranch_vccz .Lunit0_k
	v_mov_b64_e32 v[2:3], 0
	v_mov_b64_e32 v[4:5], 0
	v_mov_b64_e32 v[6:7], 0
	v_mov_b64_e32 v[8:9], 0
	v_mov_b64_e32 v[10:11], 0
	v_mov_b64_e32 v[12:13], 0
	v_mov_b64_e32 v[14:15], 0
	v_mov_b64_e32 v[16:17], 0
	v_mov_b64_e32 v[18:19], 0
	v_mov_b64_e32 v[20:21], 0
	v_mov_b64_e32 v[22:23], 0
	v_mov_b64_e32 v[24:25], 0
	v_mov_b64_e32 v[26:27], 0
	v_mov_b64_e32 v[28:29], 0
	v_mov_b64_e32 v[30:31], 0
	v_mov_b64_e32 v[32:33], 0
	v_mov_b64_e32 v[34:35], 0
	v_mov_b64_e32 v[36:37], 0
	v_mov_b64_e32 v[38:39], 0
	v_mov_b64_e32 v[40:41], 0
	v_mov_b64_e32 v[42:43], 0
	v_mov_b64_e32 v[44:45], 0
	v_mov_b64_e32 v[46:47], 0
	v_mov_b64_e32 v[48:49], 0
	v_mov_b64_e32 v[50:51], 0
	v_mov_b64_e32 v[52:53], 0
	v_mov_b64_e32 v[54:55], 0
	v_mov_b64_e32 v[56:57], 0
	v_mov_b64_e32 v[58:59], 0
	v_mov_b64_e32 v[60:61], 0
	v_mov_b64_e32 v[62:63], 0
	v_mov_b64_e32 v[64:65], 0
	v_mov_b64_e32 v[66:67], 0
	v_mov_b64_e32 v[68:69], 0
	v_mov_b64_e32 v[70:71], 0
	v_mov_b64_e32 v[72:73], 0
	v_mov_b64_e32 v[74:75], 0
	v_mov_b64_e32 v[76:77], 0
	v_mov_b64_e32 v[78:79], 0
	v_mov_b64_e32 v[80:81], 0
	v_mov_b64_e32 v[82:83], 0
	v_mov_b64_e32 v[84:85], 0
	v_mov_b64_e32 v[86:87], 0
	v_mov_b64_e32 v[88:89], 0
	v_mov_b64_e32 v[90:91], 0
	v_mov_b64_e32 v[92:93], 0
	v_mov_b64_e32 v[94:95], 0
	v_mov_b64_e32 v[96:97], 0
	v_mov_b64_e32 v[98:99], 0
	v_mov_b64_e32 v[100:101], 0
	v_mov_b64_e32 v[102:103], 0
	v_mov_b64_e32 v[104:105], 0
	v_mov_b64_e32 v[106:107], 0
	v_mov_b64_e32 v[108:109], 0
	v_mov_b64_e32 v[110:111], 0
	v_mov_b64_e32 v[112:113], 0
	v_mov_b64_e32 v[114:115], 0
	v_mov_b64_e32 v[116:117], 0
	v_mov_b64_e32 v[118:119], 0
	v_mov_b64_e32 v[120:121], 0
	v_mov_b64_e32 v[122:123], 0
	v_mov_b64_e32 v[124:125], 0
	v_mov_b64_e32 v[126:127], 0
	v_mov_b64_e32 v[128:129], 0
	s_branch .LBB0_179
.Lunit0_k:
	s_add_u32 s15, s0, 0x100
	s_addc_u32 s16, s1, 0
	s_add_u32 s0, s64, 0x80
	v_mov_b64_e32 v[2:3], 0
	v_mov_b64_e32 v[4:5], 0
	v_mov_b64_e32 v[6:7], 0
	v_mov_b64_e32 v[8:9], 0
	v_mov_b64_e32 v[10:11], 0
	v_mov_b64_e32 v[12:13], 0
	v_mov_b64_e32 v[14:15], 0
	v_mov_b64_e32 v[16:17], 0
	v_mov_b64_e32 v[18:19], 0
	v_mov_b64_e32 v[20:21], 0
	v_mov_b64_e32 v[22:23], 0
	v_mov_b64_e32 v[24:25], 0
	v_mov_b64_e32 v[26:27], 0
	v_mov_b64_e32 v[28:29], 0
	v_mov_b64_e32 v[30:31], 0
	v_mov_b64_e32 v[32:33], 0
	v_mov_b64_e32 v[34:35], 0
	v_mov_b64_e32 v[36:37], 0
	v_mov_b64_e32 v[38:39], 0
	v_mov_b64_e32 v[40:41], 0
	v_mov_b64_e32 v[42:43], 0
	v_mov_b64_e32 v[44:45], 0
	v_mov_b64_e32 v[46:47], 0
	v_mov_b64_e32 v[48:49], 0
	v_mov_b64_e32 v[50:51], 0
	v_mov_b64_e32 v[52:53], 0
	v_mov_b64_e32 v[54:55], 0
	v_mov_b64_e32 v[56:57], 0
	v_mov_b64_e32 v[58:59], 0
	v_mov_b64_e32 v[60:61], 0
	v_mov_b64_e32 v[62:63], 0
	v_mov_b64_e32 v[64:65], 0
	v_mov_b64_e32 v[66:67], 0
	v_mov_b64_e32 v[68:69], 0
	v_mov_b64_e32 v[70:71], 0
	v_mov_b64_e32 v[72:73], 0
	v_mov_b64_e32 v[74:75], 0
	v_mov_b64_e32 v[76:77], 0
	v_mov_b64_e32 v[78:79], 0
	v_mov_b64_e32 v[80:81], 0
	v_mov_b64_e32 v[82:83], 0
	v_mov_b64_e32 v[84:85], 0
	v_mov_b64_e32 v[86:87], 0
	v_mov_b64_e32 v[88:89], 0
	v_mov_b64_e32 v[90:91], 0
	v_mov_b64_e32 v[92:93], 0
	v_mov_b64_e32 v[94:95], 0
	v_mov_b64_e32 v[96:97], 0
	v_mov_b64_e32 v[98:99], 0
	v_mov_b64_e32 v[100:101], 0
	v_mov_b64_e32 v[102:103], 0
	v_mov_b64_e32 v[104:105], 0
	v_mov_b64_e32 v[106:107], 0
	v_mov_b64_e32 v[108:109], 0
	v_mov_b64_e32 v[110:111], 0
	v_mov_b64_e32 v[112:113], 0
	v_mov_b64_e32 v[114:115], 0
	v_mov_b64_e32 v[116:117], 0
	v_mov_b64_e32 v[118:119], 0
	v_mov_b64_e32 v[120:121], 0
	v_mov_b64_e32 v[122:123], 0
	v_mov_b64_e32 v[124:125], 0
	v_mov_b64_e32 v[126:127], 0
	v_mov_b64_e32 v[128:129], 0
	s_addc_u32 s1, s65, 0
	s_mov_b32 s28, 0

; template <class Epi, class Sched>
; __device__ __forceinline__ void gemm_phase(LAS unsigned char* lds, const Gemm g, const Sched& S, const Epi& E) {
;     ...
;         for (int t = 0; t < nt; t += 2) {
;             const bool last = (t == nt - 2);
;             const char* a1 = cA + (size_t)(t + 1) * kstep;
;             const char* a2 = last ? nA : cA + (size_t)(t + 2) * kstep; const char* b2 = last ? nB : cB + (size_t)(t + 2) * kstep;
;             const char* a3 = a2 + kstep; const char* b3 = b2 + kstep;
;     ...
; #pragma unroll
;         for (int a = 0; a < 2; ++a)
; #pragma unroll
;             for (int b = 0; b < 2; ++b)
; #pragma unroll
;                 for (int m = 0; m < 4; ++m)
; #pragma unroll
;                     for (int n = 0; n < 2; ++n) acc[a][b][m][n] = (f32x4){0.f, 0.f, 0.f, 0.f};
;         cur = nxt; cA = nA; cB = nB; ++ui;
.LBB0_294:
	s_andn2_b64 vcc, exec, s[62:63]
	s_cbranch_vccz .Lunit1_k
	v_mov_b32_e32 v209, 0
	v_mov_b32_e32 v208, 0
	v_mov_b32_e32 v211, 0
	v_mov_b32_e32 v210, 0
	v_mov_b32_e32 v213, 0
	v_mov_b32_e32 v212, 0
	v_mov_b32_e32 v215, 0
	v_mov_b32_e32 v214, 0
	v_mov_b32_e32 v185, 0
	v_mov_b32_e32 v184, 0
	v_mov_b32_e32 v183, 0
	v_mov_b32_e32 v182, 0
	v_mov_b32_e32 v181, 0
	v_mov_b32_e32 v180, 0
	v_mov_b32_e32 v179, 0
	v_mov_b32_e32 v178, 0
	v_mov_b32_e32 v169, 0
	v_mov_b32_e32 v168, 0
	v_mov_b32_e32 v167, 0
	v_mov_b32_e32 v166, 0
	v_mov_b32_e32 v165, 0
	v_mov_b32_e32 v164, 0
	v_mov_b32_e32 v163, 0
	v_mov_b32_e32 v162, 0
	v_mov_b32_e32 v151, 0
	v_mov_b32_e32 v150, 0
	v_mov_b32_e32 v149, 0
	v_mov_b32_e32 v148, 0
	v_mov_b32_e32 v147, 0
	v_mov_b32_e32 v146, 0
	v_mov_b32_e32 v145, 0
	v_mov_b32_e32 v144, 0
	v_mov_b32_e32 v193, 0
	v_mov_b32_e32 v192, 0
	v_mov_b32_e32 v191, 0
	v_mov_b32_e32 v190, 0
	v_mov_b32_e32 v189, 0
	v_mov_b32_e32 v188, 0
	v_mov_b32_e32 v187, 0
	v_mov_b32_e32 v186, 0
	v_mov_b32_e32 v177, 0
	v_mov_b32_e32 v176, 0
	v_mov_b32_e32 v175, 0
	v_mov_b32_e32 v174, 0
	v_mov_b32_e32 v173, 0
	v_mov_b32_e32 v172, 0
	v_mov_b32_e32 v171, 0
	v_mov_b32_e32 v170, 0
	v_mov_b32_e32 v161, 0
	v_mov_b32_e32 v160, 0
	v_mov_b32_e32 v159, 0
	v_mov_b32_e32 v158, 0
	v_mov_b32_e32 v157, 0
	v_mov_b32_e32 v156, 0
	v_mov_b32_e32 v155, 0
	v_mov_b32_e32 v154, 0
	v_mov_b32_e32 v143, 0
	v_mov_b32_e32 v142, 0
	v_mov_b32_e32 v141, 0
	v_mov_b32_e32 v140, 0
	v_mov_b32_e32 v129, 0
	v_mov_b32_e32 v128, 0
	v_mov_b32_e32 v127, 0
	v_mov_b32_e32 v126, 0
	v_mov_b32_e32 v125, 0
	v_mov_b32_e32 v124, 0
	v_mov_b32_e32 v123, 0
	v_mov_b32_e32 v122, 0
	v_mov_b32_e32 v121, 0
	v_mov_b32_e32 v120, 0
	v_mov_b32_e32 v119, 0
	v_mov_b32_e32 v118, 0
	v_mov_b32_e32 v109, 0
	v_mov_b32_e32 v108, 0
	v_mov_b32_e32 v107, 0
	v_mov_b32_e32 v106, 0
	v_mov_b32_e32 v105, 0
	v_mov_b32_e32 v104, 0
	v_mov_b32_e32 v103, 0
	v_mov_b32_e32 v102, 0
	v_mov_b32_e32 v93, 0
	v_mov_b32_e32 v92, 0
	v_mov_b32_e32 v91, 0
	v_mov_b32_e32 v90, 0
	v_mov_b32_e32 v89, 0
	v_mov_b32_e32 v88, 0
	v_mov_b32_e32 v87, 0
	v_mov_b32_e32 v86, 0
	v_mov_b32_e32 v77, 0
	v_mov_b32_e32 v76, 0
	v_mov_b32_e32 v75, 0
	v_mov_b32_e32 v74, 0
	v_mov_b32_e32 v73, 0
	v_mov_b32_e32 v72, 0
	v_mov_b32_e32 v71, 0
	v_mov_b32_e32 v70, 0
	v_mov_b32_e32 v117, 0
	v_mov_b32_e32 v116, 0
	v_mov_b32_e32 v115, 0
	v_mov_b32_e32 v114, 0
	v_mov_b32_e32 v113, 0
	v_mov_b32_e32 v112, 0
	v_mov_b32_e32 v111, 0
	v_mov_b32_e32 v110, 0
	v_mov_b32_e32 v101, 0
	v_mov_b32_e32 v100, 0
	v_mov_b32_e32 v99, 0
	v_mov_b32_e32 v98, 0
	v_mov_b32_e32 v97, 0
	v_mov_b32_e32 v96, 0
	v_mov_b32_e32 v95, 0
	v_mov_b32_e32 v94, 0
	v_mov_b32_e32 v85, 0
	v_mov_b32_e32 v84, 0
	v_mov_b32_e32 v83, 0
	v_mov_b32_e32 v82, 0
	v_mov_b32_e32 v81, 0
	v_mov_b32_e32 v80, 0
	v_mov_b32_e32 v79, 0
	v_mov_b32_e32 v78, 0
	v_mov_b32_e32 v69, 0
	v_mov_b32_e32 v68, 0
	v_mov_b32_e32 v67, 0
	v_mov_b32_e32 v66, 0
	v_mov_b32_e32 v65, 0
	v_mov_b32_e32 v64, 0
	v_mov_b32_e32 v63, 0
	v_mov_b32_e32 v62, 0
	s_branch .LBB0_298
.Lunit1_k:
	s_add_u32 s15, s0, 0x100
	s_addc_u32 s16, s1, 0
	s_add_u32 s0, s38, 0x80
	v_mov_b64_e32 v[2:3], 0
	v_mov_b64_e32 v[4:5], 0
	v_mov_b64_e32 v[6:7], 0
	v_mov_b64_e32 v[8:9], 0
	v_mov_b64_e32 v[10:11], 0
	v_mov_b64_e32 v[12:13], 0
	v_mov_b64_e32 v[14:15], 0
	v_mov_b64_e32 v[16:17], 0
	v_mov_b64_e32 v[18:19], 0
	v_mov_b64_e32 v[20:21], 0
	v_mov_b64_e32 v[22:23], 0
	v_mov_b64_e32 v[24:25], 0
	v_mov_b64_e32 v[26:27], 0
	v_mov_b64_e32 v[28:29], 0
	v_mov_b64_e32 v[30:31], 0
	v_mov_b64_e32 v[32:33], 0
	v_mov_b64_e32 v[34:35], 0
	v_mov_b64_e32 v[36:37], 0
	v_mov_b64_e32 v[38:39], 0
	v_mov_b64_e32 v[40:41], 0
	v_mov_b64_e32 v[42:43], 0
	v_mov_b64_e32 v[44:45], 0
	v_mov_b64_e32 v[46:47], 0
	v_mov_b64_e32 v[48:49], 0
	v_mov_b64_e32 v[50:51], 0
	v_mov_b64_e32 v[52:53], 0
	v_mov_b64_e32 v[54:55], 0
	v_mov_b64_e32 v[56:57], 0
	v_mov_b64_e32 v[58:59], 0
	v_mov_b64_e32 v[60:61], 0
	v_mov_b64_e32 v[62:63], 0
	v_mov_b64_e32 v[64:65], 0
	v_mov_b64_e32 v[66:67], 0
	v_mov_b64_e32 v[68:69], 0
	v_mov_b64_e32 v[70:71], 0
	v_mov_b64_e32 v[72:73], 0
	v_mov_b64_e32 v[74:75], 0
	v_mov_b64_e32 v[76:77], 0
	v_mov_b64_e32 v[78:79], 0
	v_mov_b64_e32 v[80:81], 0
	v_mov_b64_e32 v[82:83], 0
	v_mov_b64_e32 v[84:85], 0
	v_mov_b64_e32 v[86:87], 0
	v_mov_b64_e32 v[88:89], 0
	v_mov_b64_e32 v[90:91], 0
	v_mov_b64_e32 v[92:93], 0
	v_mov_b64_e32 v[94:95], 0
	v_mov_b64_e32 v[96:97], 0
	v_mov_b64_e32 v[98:99], 0
	v_mov_b64_e32 v[100:101], 0
	v_mov_b64_e32 v[102:103], 0
	v_mov_b64_e32 v[104:105], 0
	v_mov_b64_e32 v[106:107], 0
	v_mov_b64_e32 v[108:109], 0
	v_mov_b64_e32 v[110:111], 0
	v_mov_b64_e32 v[112:113], 0
	v_mov_b64_e32 v[114:115], 0
	v_mov_b64_e32 v[116:117], 0
	v_mov_b64_e32 v[118:119], 0
	v_mov_b64_e32 v[120:121], 0
	v_mov_b64_e32 v[122:123], 0
	v_mov_b64_e32 v[124:125], 0
	v_mov_b64_e32 v[126:127], 0
	v_mov_b64_e32 v[128:129], 0
	s_addc_u32 s1, s39, 0
	s_mov_b32 s28, 0

; template <class Epi, class Sched>
; __device__ __forceinline__ void gemm_phase(LAS unsigned char* lds, const Gemm g, const Sched& S, const Epi& E) {
;     ...
;         for (int t = 0; t < nt; t += 2) {
;             const bool last = (t == nt - 2);
;             const char* a1 = cA + (size_t)(t + 1) * kstep;
;             const char* a2 = last ? nA : cA + (size_t)(t + 2) * kstep; const char* b2 = last ? nB : cB + (size_t)(t + 2) * kstep;
;             const char* a3 = a2 + kstep; const char* b3 = b2 + kstep;
;     ...
; #pragma unroll
;         for (int a = 0; a < 2; ++a)
; #pragma unroll
;             for (int b = 0; b < 2; ++b)
; #pragma unroll
;                 for (int m = 0; m < 4; ++m)
; #pragma unroll
;                     for (int n = 0; n < 2; ++n) acc[a][b][m][n] = (f32x4){0.f, 0.f, 0.f, 0.f};
;         cur = nxt; cA = nA; cB = nB; ++ui;
.LBB0_426:
	s_andn2_b64 vcc, exec, s[60:61]
	s_cbranch_vccz .Lunit2_k
	v_mov_b64_e32 v[2:3], 0
	v_mov_b64_e32 v[4:5], 0
	v_mov_b64_e32 v[6:7], 0
	v_mov_b64_e32 v[8:9], 0
	v_mov_b64_e32 v[10:11], 0
	v_mov_b64_e32 v[12:13], 0
	v_mov_b64_e32 v[14:15], 0
	v_mov_b64_e32 v[16:17], 0
	v_mov_b64_e32 v[18:19], 0
	v_mov_b64_e32 v[20:21], 0
	v_mov_b64_e32 v[22:23], 0
	v_mov_b64_e32 v[24:25], 0
	v_mov_b64_e32 v[26:27], 0
	v_mov_b64_e32 v[28:29], 0
	v_mov_b64_e32 v[30:31], 0
	v_mov_b64_e32 v[32:33], 0
	v_mov_b64_e32 v[34:35], 0
	v_mov_b64_e32 v[36:37], 0
	v_mov_b64_e32 v[38:39], 0
	v_mov_b64_e32 v[40:41], 0
	v_mov_b64_e32 v[42:43], 0
	v_mov_b64_e32 v[44:45], 0
	v_mov_b64_e32 v[46:47], 0
	v_mov_b64_e32 v[48:49], 0
	v_mov_b64_e32 v[50:51], 0
	v_mov_b64_e32 v[52:53], 0
	v_mov_b64_e32 v[54:55], 0
	v_mov_b64_e32 v[56:57], 0
	v_mov_b64_e32 v[58:59], 0
	v_mov_b64_e32 v[60:61], 0
	v_mov_b64_e32 v[62:63], 0
	v_mov_b64_e32 v[64:65], 0
	v_mov_b64_e32 v[66:67], 0
	v_mov_b64_e32 v[68:69], 0
	v_mov_b64_e32 v[70:71], 0
	v_mov_b64_e32 v[72:73], 0
	v_mov_b64_e32 v[74:75], 0
	v_mov_b64_e32 v[76:77], 0
	v_mov_b64_e32 v[78:79], 0
	v_mov_b64_e32 v[80:81], 0
	v_mov_b64_e32 v[82:83], 0
	v_mov_b64_e32 v[84:85], 0
	v_mov_b64_e32 v[86:87], 0
	v_mov_b64_e32 v[88:89], 0
	v_mov_b64_e32 v[90:91], 0
	v_mov_b64_e32 v[92:93], 0
	v_mov_b64_e32 v[94:95], 0
	v_mov_b64_e32 v[96:97], 0
	v_mov_b64_e32 v[98:99], 0
	v_mov_b64_e32 v[100:101], 0
	v_mov_b64_e32 v[102:103], 0
	v_mov_b64_e32 v[104:105], 0
	v_mov_b64_e32 v[106:107], 0
	v_mov_b64_e32 v[108:109], 0
	v_mov_b64_e32 v[110:111], 0
	v_mov_b64_e32 v[112:113], 0
	v_mov_b64_e32 v[114:115], 0
	v_mov_b64_e32 v[116:117], 0
	v_mov_b64_e32 v[118:119], 0
	v_mov_b64_e32 v[120:121], 0
	v_mov_b64_e32 v[122:123], 0
	v_mov_b64_e32 v[124:125], 0
	v_mov_b64_e32 v[126:127], 0
	v_mov_b64_e32 v[128:129], 0
	s_branch .LBB0_429

; template <class Epi, class Sched>
; __device__ __forceinline__ void gemm_phase(LAS unsigned char* lds, const Gemm g, const Sched& S, const Epi& E) {
;     ...
;         for (int t = 0; t < nt; t += 2) {
;             const bool last = (t == nt - 2);
;             const char* a1 = cA + (size_t)(t + 1) * kstep;
;             const char* a2 = last ? nA : cA + (size_t)(t + 2) * kstep; const char* b2 = last ? nB : cB + (size_t)(t + 2) * kstep;
;             const char* a3 = a2 + kstep; const char* b3 = b2 + kstep;
;     ...
; #pragma unroll
;         for (int a = 0; a < 2; ++a)
; #pragma unroll
;             for (int b = 0; b < 2; ++b)
; #pragma unroll
;                 for (int m = 0; m < 4; ++m)
; #pragma unroll
;                     for (int n = 0; n < 2; ++n) acc[a][b][m][n] = (f32x4){0.f, 0.f, 0.f, 0.f};
;         cur = nxt; cA = nA; cB = nB; ++ui;
.LBB0_1438:
	s_andn2_b64 vcc, exec, s[64:65]
	s_cbranch_vccz .Lunit3_k
	v_mov_b64_e32 v[2:3], 0
	v_mov_b64_e32 v[4:5], 0
	v_mov_b64_e32 v[6:7], 0
	v_mov_b64_e32 v[8:9], 0
	v_mov_b64_e32 v[10:11], 0
	v_mov_b64_e32 v[12:13], 0
	v_mov_b64_e32 v[14:15], 0
	v_mov_b64_e32 v[16:17], 0
	v_mov_b64_e32 v[18:19], 0
	v_mov_b64_e32 v[20:21], 0
	v_mov_b64_e32 v[22:23], 0
	v_mov_b64_e32 v[24:25], 0
	v_mov_b64_e32 v[26:27], 0
	v_mov_b64_e32 v[28:29], 0
	v_mov_b64_e32 v[30:31], 0
	v_mov_b64_e32 v[32:33], 0
	v_mov_b64_e32 v[34:35], 0
	v_mov_b64_e32 v[36:37], 0
	v_mov_b64_e32 v[38:39], 0
	v_mov_b64_e32 v[40:41], 0
	v_mov_b64_e32 v[42:43], 0
	v_mov_b64_e32 v[44:45], 0
	v_mov_b64_e32 v[46:47], 0
	v_mov_b64_e32 v[48:49], 0
	v_mov_b64_e32 v[50:51], 0
	v_mov_b64_e32 v[52:53], 0
	v_mov_b64_e32 v[54:55], 0
	v_mov_b64_e32 v[56:57], 0
	v_mov_b64_e32 v[58:59], 0
	v_mov_b64_e32 v[60:61], 0
	v_mov_b64_e32 v[62:63], 0
	v_mov_b64_e32 v[64:65], 0
	v_mov_b64_e32 v[66:67], 0
	v_mov_b64_e32 v[68:69], 0
	v_mov_b64_e32 v[70:71], 0
	v_mov_b64_e32 v[72:73], 0
	v_mov_b64_e32 v[74:75], 0
	v_mov_b64_e32 v[76:77], 0
	v_mov_b64_e32 v[78:79], 0
	v_mov_b64_e32 v[80:81], 0
	v_mov_b64_e32 v[82:83], 0
	v_mov_b64_e32 v[84:85], 0
	v_mov_b64_e32 v[86:87], 0
	v_mov_b64_e32 v[88:89], 0
	v_mov_b64_e32 v[90:91], 0
	v_mov_b64_e32 v[92:93], 0
	v_mov_b64_e32 v[94:95], 0
	v_mov_b64_e32 v[96:97], 0
	v_mov_b64_e32 v[98:99], 0
	v_mov_b64_e32 v[100:101], 0
	v_mov_b64_e32 v[102:103], 0
	v_mov_b64_e32 v[104:105], 0
	v_mov_b64_e32 v[106:107], 0
	v_mov_b64_e32 v[108:109], 0
	v_mov_b64_e32 v[110:111], 0
	v_mov_b64_e32 v[112:113], 0
	v_mov_b64_e32 v[114:115], 0
	v_mov_b64_e32 v[116:117], 0
	v_mov_b64_e32 v[118:119], 0
	v_mov_b64_e32 v[120:121], 0
	v_mov_b64_e32 v[122:123], 0
	v_mov_b64_e32 v[124:125], 0
	v_mov_b64_e32 v[126:127], 0
	v_mov_b64_e32 v[128:129], 0
	s_branch .LBB0_1441

; template <class Epi, class Sched>
; __device__ __forceinline__ void gemm_phase(LAS unsigned char* lds, const Gemm g, const Sched& S, const Epi& E) {
;     ...
;         for (int t = 0; t < nt; t += 2) {
;             const bool last = (t == nt - 2);
;             const char* a1 = cA + (size_t)(t + 1) * kstep;
;             const char* a2 = last ? nA : cA + (size_t)(t + 2) * kstep; const char* b2 = last ? nB : cB + (size_t)(t + 2) * kstep;
;             const char* a3 = a2 + kstep; const char* b3 = b2 + kstep;
;     ...
; #pragma unroll
;         for (int a = 0; a < 2; ++a)
; #pragma unroll
;             for (int b = 0; b < 2; ++b)
; #pragma unroll
;                 for (int m = 0; m < 4; ++m)
; #pragma unroll
;                     for (int n = 0; n < 2; ++n) acc[a][b][m][n] = (f32x4){0.f, 0.f, 0.f, 0.f};
;         cur = nxt; cA = nA; cB = nB; ++ui;
.LBB0_1774:
	s_andn2_b64 vcc, exec, s[62:63]
	s_cbranch_vccz .Lunit5_k
	v_mov_b64_e32 v[2:3], 0
	v_mov_b64_e32 v[4:5], 0
	v_mov_b64_e32 v[6:7], 0
	v_mov_b64_e32 v[8:9], 0
	v_mov_b64_e32 v[10:11], 0
	v_mov_b64_e32 v[12:13], 0
	v_mov_b64_e32 v[14:15], 0
	v_mov_b64_e32 v[16:17], 0
	v_mov_b64_e32 v[18:19], 0
	v_mov_b64_e32 v[20:21], 0
	v_mov_b64_e32 v[22:23], 0
	v_mov_b64_e32 v[24:25], 0
	v_mov_b64_e32 v[26:27], 0
	v_mov_b64_e32 v[28:29], 0
	v_mov_b64_e32 v[30:31], 0
	v_mov_b64_e32 v[32:33], 0
	v_mov_b64_e32 v[34:35], 0
	v_mov_b64_e32 v[36:37], 0
	v_mov_b64_e32 v[38:39], 0
	v_mov_b64_e32 v[40:41], 0
	v_mov_b64_e32 v[42:43], 0
	v_mov_b64_e32 v[44:45], 0
	v_mov_b64_e32 v[46:47], 0
	v_mov_b64_e32 v[48:49], 0
	v_mov_b64_e32 v[50:51], 0
	v_mov_b64_e32 v[52:53], 0
	v_mov_b64_e32 v[54:55], 0
	v_mov_b64_e32 v[56:57], 0
	v_mov_b64_e32 v[58:59], 0
	v_mov_b64_e32 v[60:61], 0
	v_mov_b64_e32 v[62:63], 0
	v_mov_b64_e32 v[64:65], 0
	v_mov_b64_e32 v[66:67], 0
	v_mov_b64_e32 v[68:69], 0
	v_mov_b64_e32 v[70:71], 0
	v_mov_b64_e32 v[72:73], 0
	v_mov_b64_e32 v[74:75], 0
	v_mov_b64_e32 v[76:77], 0
	v_mov_b64_e32 v[78:79], 0
	v_mov_b64_e32 v[80:81], 0
	v_mov_b64_e32 v[82:83], 0
	v_mov_b64_e32 v[84:85], 0
	v_mov_b64_e32 v[86:87], 0
	v_mov_b64_e32 v[88:89], 0
	v_mov_b64_e32 v[90:91], 0
	v_mov_b64_e32 v[92:93], 0
	v_mov_b64_e32 v[94:95], 0
	v_mov_b64_e32 v[96:97], 0
	v_mov_b64_e32 v[98:99], 0
	v_mov_b64_e32 v[100:101], 0
	v_mov_b64_e32 v[102:103], 0
	v_mov_b64_e32 v[104:105], 0
	v_mov_b64_e32 v[106:107], 0
	v_mov_b64_e32 v[108:109], 0
	v_mov_b64_e32 v[110:111], 0
	v_mov_b64_e32 v[112:113], 0
	v_mov_b64_e32 v[114:115], 0
	v_mov_b64_e32 v[116:117], 0
	v_mov_b64_e32 v[118:119], 0
	v_mov_b64_e32 v[120:121], 0
	v_mov_b64_e32 v[122:123], 0
	v_mov_b64_e32 v[124:125], 0
	v_mov_b64_e32 v[126:127], 0
	v_mov_b64_e32 v[128:129], 0
	s_branch .LBB0_1778

; template <class Epi, class Sched>
; __device__ __forceinline__ void gemm_phase(LAS unsigned char* lds, const Gemm g, const Sched& S, const Epi& E) {
;     ...
;         for (int t = 0; t < nt; t += 2) {
;             const bool last = (t == nt - 2);
;             const char* a1 = cA + (size_t)(t + 1) * kstep;
;             const char* a2 = last ? nA : cA + (size_t)(t + 2) * kstep; const char* b2 = last ? nB : cB + (size_t)(t + 2) * kstep;
;             const char* a3 = a2 + kstep; const char* b3 = b2 + kstep;
;     ...
; #pragma unroll
;         for (int a = 0; a < 2; ++a)
; #pragma unroll
;             for (int b = 0; b < 2; ++b)
; #pragma unroll
;                 for (int m = 0; m < 4; ++m)
; #pragma unroll
;                     for (int n = 0; n < 2; ++n) acc[a][b][m][n] = (f32x4){0.f, 0.f, 0.f, 0.f};
;         cur = nxt; cA = nA; cB = nB; ++ui;
.LBB0_2024:
	s_andn2_b64 vcc, exec, s[58:59]
	s_cbranch_vccz .Lunit7_k
	v_mov_b32_e32 v209, 0
	v_mov_b32_e32 v208, 0
	v_mov_b32_e32 v211, 0
	v_mov_b32_e32 v210, 0
	v_mov_b32_e32 v213, 0
	v_mov_b32_e32 v212, 0
	v_mov_b32_e32 v215, 0
	v_mov_b32_e32 v214, 0
	v_mov_b32_e32 v185, 0
	v_mov_b32_e32 v184, 0
	v_mov_b32_e32 v183, 0
	v_mov_b32_e32 v182, 0
	v_mov_b32_e32 v181, 0
	v_mov_b32_e32 v180, 0
	v_mov_b32_e32 v179, 0
	v_mov_b32_e32 v178, 0
	v_mov_b32_e32 v169, 0
	v_mov_b32_e32 v168, 0
	v_mov_b32_e32 v167, 0
	v_mov_b32_e32 v166, 0
	v_mov_b32_e32 v165, 0
	v_mov_b32_e32 v164, 0
	v_mov_b32_e32 v163, 0
	v_mov_b32_e32 v162, 0
	v_mov_b32_e32 v151, 0
	v_mov_b32_e32 v150, 0
	v_mov_b32_e32 v149, 0
	v_mov_b32_e32 v148, 0
	v_mov_b32_e32 v147, 0
	v_mov_b32_e32 v146, 0
	v_mov_b32_e32 v145, 0
	v_mov_b32_e32 v144, 0
	v_mov_b32_e32 v193, 0
	v_mov_b32_e32 v192, 0
	v_mov_b32_e32 v191, 0
	v_mov_b32_e32 v190, 0
	v_mov_b32_e32 v189, 0
	v_mov_b32_e32 v188, 0
	v_mov_b32_e32 v187, 0
	v_mov_b32_e32 v186, 0
	v_mov_b32_e32 v177, 0
	v_mov_b32_e32 v176, 0
	v_mov_b32_e32 v175, 0
	v_mov_b32_e32 v174, 0
	v_mov_b32_e32 v173, 0
	v_mov_b32_e32 v172, 0
	v_mov_b32_e32 v171, 0
	v_mov_b32_e32 v170, 0
	v_mov_b32_e32 v161, 0
	v_mov_b32_e32 v160, 0
	v_mov_b32_e32 v159, 0
	v_mov_b32_e32 v158, 0
	v_mov_b32_e32 v157, 0
	v_mov_b32_e32 v156, 0
	v_mov_b32_e32 v155, 0
	v_mov_b32_e32 v154, 0
	v_mov_b32_e32 v143, 0
	v_mov_b32_e32 v142, 0
	v_mov_b32_e32 v141, 0
	v_mov_b32_e32 v140, 0
	v_mov_b32_e32 v129, 0
	v_mov_b32_e32 v128, 0
	v_mov_b32_e32 v127, 0
	v_mov_b32_e32 v126, 0
	v_mov_b32_e32 v125, 0
	v_mov_b32_e32 v124, 0
	v_mov_b32_e32 v123, 0
	v_mov_b32_e32 v122, 0
	v_mov_b32_e32 v121, 0
	v_mov_b32_e32 v120, 0
	v_mov_b32_e32 v119, 0
	v_mov_b32_e32 v118, 0
	v_mov_b32_e32 v109, 0
	v_mov_b32_e32 v108, 0
	v_mov_b32_e32 v107, 0
	v_mov_b32_e32 v106, 0
	v_mov_b32_e32 v105, 0
	v_mov_b32_e32 v104, 0
	v_mov_b32_e32 v103, 0
	v_mov_b32_e32 v102, 0
	v_mov_b32_e32 v93, 0
	v_mov_b32_e32 v92, 0
	v_mov_b32_e32 v91, 0
	v_mov_b32_e32 v90, 0
	v_mov_b32_e32 v89, 0
	v_mov_b32_e32 v88, 0
	v_mov_b32_e32 v87, 0
	v_mov_b32_e32 v86, 0
	v_mov_b32_e32 v77, 0
	v_mov_b32_e32 v76, 0
	v_mov_b32_e32 v75, 0
	v_mov_b32_e32 v74, 0
	v_mov_b32_e32 v73, 0
	v_mov_b32_e32 v72, 0
	v_mov_b32_e32 v71, 0
	v_mov_b32_e32 v70, 0
	v_mov_b32_e32 v117, 0
	v_mov_b32_e32 v116, 0
	v_mov_b32_e32 v115, 0
	v_mov_b32_e32 v114, 0
	v_mov_b32_e32 v113, 0
	v_mov_b32_e32 v112, 0
	v_mov_b32_e32 v111, 0
	v_mov_b32_e32 v110, 0
	v_mov_b32_e32 v101, 0
	v_mov_b32_e32 v100, 0
	v_mov_b32_e32 v99, 0
	v_mov_b32_e32 v98, 0
	v_mov_b32_e32 v97, 0
	v_mov_b32_e32 v96, 0
	v_mov_b32_e32 v95, 0
	v_mov_b32_e32 v94, 0
	v_mov_b32_e32 v85, 0
	v_mov_b32_e32 v84, 0
	v_mov_b32_e32 v83, 0
	v_mov_b32_e32 v82, 0
	v_mov_b32_e32 v81, 0
	v_mov_b32_e32 v80, 0
	v_mov_b32_e32 v79, 0
	v_mov_b32_e32 v78, 0
	v_mov_b32_e32 v69, 0
	v_mov_b32_e32 v68, 0
	v_mov_b32_e32 v67, 0
	v_mov_b32_e32 v66, 0
	v_mov_b32_e32 v65, 0
	v_mov_b32_e32 v64, 0
	v_mov_b32_e32 v63, 0
	v_mov_b32_e32 v62, 0
	s_branch .LBB0_2028
